# S5 pass-2 output projection: 8 LDS fragment reads issued together, MFMAs gated by counted lgkmcnt waits
# speedup vs baseline: 1.0073x; 1.0073x over previous
; DI bf16_t f2bf(float x) { unsigned u = __float_as_uint(x); u += 0x7fffu + ((u >> 16) & 1u); return (bf16_t)(u >> 16); }
; template <bool PASS2>
; DI void s5_item(const Params& p, int l, int item, int lane, const bf16_t* ubuf, bf16_t* ybpre, bf16_t* xs, float* bus) {
;     ...
;     const bf16x8 uf = *(const bf16x8*)(ubuf + (tok0 + tb + r) * 512 + g * 16 + 8 * hh);
;     f32x16 D[4];
; #pragma unroll
;     for (int mt = 0; mt < 4; mt++) {
; #pragma unroll
;       for (int i = 0; i < 16; i++) D[mt][i] = 0.f;
;       D[mt] = __builtin_amdgcn_mfma_f32_32x32x16_bf16(bf_[mt], uf, D[mt], 0, 0, 0);
;     }
; #pragma unroll
;     for (int half = 0; half < 2; half++) {
;       __builtin_amdgcn_fence(__ATOMIC_RELEASE, "wavefront");
;       __builtin_amdgcn_wave_barrier();
;       if ((r >> 4) == half) {
; #pragma unroll
;         for (int mt = 0; mt < 4; mt++)
; #pragma unroll
;           for (int i = 0; i < 16; i++)
;             bus[(32 * mt + (i & 3) + 8 * (i >> 2) + 4 * hh) * 17 + (r & 15)] = D[mt][i];
;       }
;       __builtin_amdgcn_fence(__ATOMIC_RELEASE, "wavefront");
;       __builtin_amdgcn_wave_barrier();
;       __builtin_amdgcn_fence(__ATOMIC_ACQUIRE, "wavefront");
; #pragma unroll 4
;       for (int t = 0; t < 16; t++) {
;         const float bur = bus[lane * 17 + t], bui = bus[(64 + lane) * 17 + t];
;         const float nxr = ar * xr - ai * xi + bur, nxi = ar * xi + ai * xr + bui;
;         xr = nxr; xi = nxi;
;         if (PASS2) {
;           xs[(half * 16 + t) * XSP + lane] = f2bf(xr);
;           xs[(half * 16 + t) * XSP + 64 + lane] = f2bf(xi);
;         }
;       }
.LBB0_786:
	v_lshl_add_u64 v[140:141], v[130:131], 0, s[10:11]
	v_lshlrev_b64 v[0:1], 10, v[140:141]
	v_lshl_add_u64 v[138:139], s[4:5], 0, v[0:1]
	v_lshl_add_u64 v[0:1], v[138:139], 0, v[114:115]
	v_lshl_add_u64 v[208:209], v[0:1], 0, s[98:99]
	v_mov_b32_e32 v206, v124
	v_mov_b32_e32 v207, v115
	v_lshl_add_u64 v[206:207], v[138:139], 0, v[206:207]
	global_load_dwordx2 v[220:221], v[206:207], off
	global_load_dwordx2 v[222:223], v[206:207], off offset:16
	v_add_u32_e32 v190, 0x8800, v144
	v_add_u32_e32 v189, 0x8c00, v144
	v_add_u32_e32 v187, 0x9000, v144
	v_add_u32_e32 v188, 0x9400, v144
	v_add_u32_e32 v186, 0x9800, v144
	v_add_u32_e32 v184, 0x9c00, v144
	v_add_u32_e32 v185, 0x9e00, v144
	v_add_u32_e32 v183, 0xa000, v144
	v_add_u32_e32 v125, 0xa400, v144
	v_add_u32_e32 v181, 0xa600, v144
	v_add_u32_e32 v182, 0xa800, v144
	s_waitcnt vmcnt(4)
	v_mfma_f32_32x32x16_bf16 v[48:63], v[202:205], v[64:67], 0
	v_mfma_f32_32x32x16_bf16 v[32:47], v[202:205], v[68:71], 0
	v_mfma_f32_32x32x16_bf16 v[0:15], v[202:205], v[72:75], 0
	v_mfma_f32_32x32x16_bf16 v[16:31], v[202:205], v[76:79], 0
	global_load_dwordx4 v[202:205], v[208:209], off
	v_lshlrev_b64 v[140:141], 9, v[140:141]
	s_nop 7
	s_nop 1
	v_permlane32_swap_b32 v48, v32
	v_permlane32_swap_b32 v49, v33
	v_permlane32_swap_b32 v50, v34
	v_permlane32_swap_b32 v51, v35
	v_permlane32_swap_b32 v52, v36
	v_permlane32_swap_b32 v53, v37
	v_permlane32_swap_b32 v54, v38
	v_permlane32_swap_b32 v55, v39
	v_permlane32_swap_b32 v56, v40
	v_permlane32_swap_b32 v57, v41
	v_permlane32_swap_b32 v58, v42
	v_permlane32_swap_b32 v59, v43
	v_permlane32_swap_b32 v60, v44
	v_permlane32_swap_b32 v61, v45
	v_permlane32_swap_b32 v62, v46
	v_permlane32_swap_b32 v63, v47
	v_permlane32_swap_b32 v0, v16
	v_permlane32_swap_b32 v1, v17
	v_permlane32_swap_b32 v2, v18
	v_permlane32_swap_b32 v3, v19
	v_permlane32_swap_b32 v4, v20
	v_permlane32_swap_b32 v5, v21
	v_permlane32_swap_b32 v6, v22
	v_permlane32_swap_b32 v7, v23
	v_permlane32_swap_b32 v8, v24
	v_permlane32_swap_b32 v9, v25
	v_permlane32_swap_b32 v10, v26
	v_permlane32_swap_b32 v11, v27
	v_permlane32_swap_b32 v12, v28
	v_permlane32_swap_b32 v13, v29
	v_permlane32_swap_b32 v14, v30
	v_permlane32_swap_b32 v15, v31
	v_fma_f32 v194, v126, v128, v48
	v_fma_f32 v195, v126, v129, v0
	v_fma_f32 v194, -v127, v129, v194
	v_fma_f32 v195, v127, v128, v195
	v_bfe_u32 v196, v194, 16, 1
	v_bfe_u32 v197, v195, 16, 1
	v_add3_u32 v196, v194, v196, s22
	v_add3_u32 v197, v195, v197, s22
	ds_write_b16_d16_hi v145, v196 offset:0
	ds_write_b16_d16_hi v145, v197 offset:128
	v_fma_f32 v128, v126, v194, v49
	v_fma_f32 v129, v126, v195, v1
	v_fma_f32 v128, -v127, v195, v128
	v_fma_f32 v129, v127, v194, v129
	v_bfe_u32 v196, v128, 16, 1
	v_bfe_u32 v197, v129, 16, 1
	v_add3_u32 v196, v128, v196, s22
	v_add3_u32 v197, v129, v197, s22
	ds_write_b16_d16_hi v145, v196 offset:272
	ds_write_b16_d16_hi v145, v197 offset:400
	v_fma_f32 v194, v126, v128, v50
	v_fma_f32 v195, v126, v129, v2
	v_fma_f32 v194, -v127, v129, v194
	v_fma_f32 v195, v127, v128, v195
	v_bfe_u32 v196, v194, 16, 1
	v_bfe_u32 v197, v195, 16, 1
	v_add3_u32 v196, v194, v196, s22
	v_add3_u32 v197, v195, v197, s22
	ds_write_b16_d16_hi v145, v196 offset:544
	ds_write_b16_d16_hi v145, v197 offset:672
	v_fma_f32 v128, v126, v194, v51
	v_fma_f32 v129, v126, v195, v3
	v_fma_f32 v128, -v127, v195, v128
	v_fma_f32 v129, v127, v194, v129
	v_bfe_u32 v196, v128, 16, 1
	v_bfe_u32 v197, v129, 16, 1
	v_add3_u32 v196, v128, v196, s22
	v_add3_u32 v197, v129, v197, s22
	ds_write_b16_d16_hi v145, v196 offset:816
	ds_write_b16_d16_hi v145, v197 offset:944
	v_fma_f32 v194, v126, v128, v32
	v_fma_f32 v195, v126, v129, v16
	v_fma_f32 v194, -v127, v129, v194
	v_fma_f32 v195, v127, v128, v195
	v_bfe_u32 v196, v194, 16, 1
	v_bfe_u32 v197, v195, 16, 1
	v_add3_u32 v196, v194, v196, s22
	v_add3_u32 v197, v195, v197, s22
	ds_write_b16_d16_hi v145, v196 offset:1088
	ds_write_b16_d16_hi v145, v197 offset:1216
	v_fma_f32 v128, v126, v194, v33
	v_fma_f32 v129, v126, v195, v17
	v_fma_f32 v128, -v127, v195, v128
	v_fma_f32 v129, v127, v194, v129
	v_bfe_u32 v196, v128, 16, 1
	v_bfe_u32 v197, v129, 16, 1
	v_add3_u32 v196, v128, v196, s22
	v_add3_u32 v197, v129, v197, s22
	ds_write_b16_d16_hi v145, v196 offset:1360
	ds_write_b16_d16_hi v145, v197 offset:1488
	v_fma_f32 v194, v126, v128, v34
	v_fma_f32 v195, v126, v129, v18
	v_fma_f32 v194, -v127, v129, v194
	v_fma_f32 v195, v127, v128, v195
	v_bfe_u32 v196, v194, 16, 1
	v_bfe_u32 v197, v195, 16, 1
	v_add3_u32 v196, v194, v196, s22
	v_add3_u32 v197, v195, v197, s22
	ds_write_b16_d16_hi v145, v196 offset:1632
	ds_write_b16_d16_hi v145, v197 offset:1760
	v_fma_f32 v128, v126, v194, v35
	v_fma_f32 v129, v126, v195, v19
	v_fma_f32 v128, -v127, v195, v128
	v_fma_f32 v129, v127, v194, v129
	v_bfe_u32 v196, v128, 16, 1
	v_bfe_u32 v197, v129, 16, 1
	v_add3_u32 v196, v128, v196, s22
	v_add3_u32 v197, v129, v197, s22
	ds_write_b16_d16_hi v145, v196 offset:1904
	ds_write_b16_d16_hi v145, v197 offset:2032
	v_fma_f32 v194, v126, v128, v52
	v_fma_f32 v195, v126, v129, v4
	v_fma_f32 v194, -v127, v129, v194
	v_fma_f32 v195, v127, v128, v195
	v_bfe_u32 v196, v194, 16, 1
	v_bfe_u32 v197, v195, 16, 1
	v_add3_u32 v196, v194, v196, s22
	v_add3_u32 v197, v195, v197, s22
	ds_write_b16_d16_hi v145, v196 offset:2176
	ds_write_b16_d16_hi v145, v197 offset:2304
	v_fma_f32 v128, v126, v194, v53
	v_fma_f32 v129, v126, v195, v5
	v_fma_f32 v128, -v127, v195, v128
	v_fma_f32 v129, v127, v194, v129
	v_bfe_u32 v196, v128, 16, 1
	v_bfe_u32 v197, v129, 16, 1
	v_add3_u32 v196, v128, v196, s22
	v_add3_u32 v197, v129, v197, s22
	ds_write_b16_d16_hi v145, v196 offset:2448
; DI bf16_t f2bf(float x) { unsigned u = __float_as_uint(x); u += 0x7fffu + ((u >> 16) & 1u); return (bf16_t)(u >> 16); }
; template <bool PASS2>
; DI void s5_item(const Params& p, int l, int item, int lane, const bf16_t* ubuf, bf16_t* ybpre, bf16_t* xs, float* bus) {
;     ...
; #pragma unroll 4
;       for (int t = 0; t < 16; t++) {
;         const float bur = bus[lane * 17 + t], bui = bus[(64 + lane) * 17 + t];
;         const float nxr = ar * xr - ai * xi + bur, nxi = ar * xi + ai * xr + bui;
;         xr = nxr; xi = nxi;
;         if (PASS2) {
;           xs[(half * 16 + t) * XSP + lane] = f2bf(xr);
;           xs[(half * 16 + t) * XSP + 64 + lane] = f2bf(xi);
;         }
;       }
	ds_write_b16_d16_hi v145, v197 offset:2576
	v_fma_f32 v194, v126, v128, v54
	v_fma_f32 v195, v126, v129, v6
	v_fma_f32 v194, -v127, v129, v194
	v_fma_f32 v195, v127, v128, v195
	v_bfe_u32 v196, v194, 16, 1
	v_bfe_u32 v197, v195, 16, 1
	v_add3_u32 v196, v194, v196, s22
	v_add3_u32 v197, v195, v197, s22
	ds_write_b16_d16_hi v145, v196 offset:2720
	ds_write_b16_d16_hi v145, v197 offset:2848
	v_fma_f32 v128, v126, v194, v55
	v_fma_f32 v129, v126, v195, v7
	v_fma_f32 v128, -v127, v195, v128
	v_fma_f32 v129, v127, v194, v129
	v_bfe_u32 v196, v128, 16, 1
	v_bfe_u32 v197, v129, 16, 1
	v_add3_u32 v196, v128, v196, s22
	v_add3_u32 v197, v129, v197, s22
	ds_write_b16_d16_hi v145, v196 offset:2992
	ds_write_b16_d16_hi v145, v197 offset:3120
	v_fma_f32 v194, v126, v128, v36
	v_fma_f32 v195, v126, v129, v20
	v_fma_f32 v194, -v127, v129, v194
	v_fma_f32 v195, v127, v128, v195
	v_bfe_u32 v196, v194, 16, 1
	v_bfe_u32 v197, v195, 16, 1
	v_add3_u32 v196, v194, v196, s22
	v_add3_u32 v197, v195, v197, s22
	ds_write_b16_d16_hi v145, v196 offset:3264
	ds_write_b16_d16_hi v145, v197 offset:3392
	v_fma_f32 v128, v126, v194, v37
	v_fma_f32 v129, v126, v195, v21
	v_fma_f32 v128, -v127, v195, v128
	v_fma_f32 v129, v127, v194, v129
	v_bfe_u32 v196, v128, 16, 1
	v_bfe_u32 v197, v129, 16, 1
	v_add3_u32 v196, v128, v196, s22
	v_add3_u32 v197, v129, v197, s22
	ds_write_b16_d16_hi v145, v196 offset:3536
	ds_write_b16_d16_hi v145, v197 offset:3664
	v_fma_f32 v194, v126, v128, v38
	v_fma_f32 v195, v126, v129, v22
	v_fma_f32 v194, -v127, v129, v194
	v_fma_f32 v195, v127, v128, v195
	v_bfe_u32 v196, v194, 16, 1
	v_bfe_u32 v197, v195, 16, 1
	v_add3_u32 v196, v194, v196, s22
	v_add3_u32 v197, v195, v197, s22
	ds_write_b16_d16_hi v145, v196 offset:3808
	ds_write_b16_d16_hi v145, v197 offset:3936
	v_fma_f32 v128, v126, v194, v39
	v_fma_f32 v129, v126, v195, v23
	v_fma_f32 v128, -v127, v195, v128
	v_fma_f32 v129, v127, v194, v129
	v_bfe_u32 v196, v128, 16, 1
	v_bfe_u32 v197, v129, 16, 1
	v_add3_u32 v196, v128, v196, s22
	v_add3_u32 v197, v129, v197, s22
	ds_write_b16_d16_hi v145, v196 offset:4080
	ds_write_b16_d16_hi v145, v197 offset:4208
	v_fma_f32 v194, v126, v128, v56
	v_fma_f32 v195, v126, v129, v8
	v_fma_f32 v194, -v127, v129, v194
	v_fma_f32 v195, v127, v128, v195
	v_bfe_u32 v196, v194, 16, 1
	v_bfe_u32 v197, v195, 16, 1
	v_add3_u32 v196, v194, v196, s22
	v_add3_u32 v197, v195, v197, s22
	ds_write_b16_d16_hi v145, v196 offset:4352
	ds_write_b16_d16_hi v145, v197 offset:4480
	v_fma_f32 v128, v126, v194, v57
	v_fma_f32 v129, v126, v195, v9
	v_fma_f32 v128, -v127, v195, v128
	v_fma_f32 v129, v127, v194, v129
	v_bfe_u32 v196, v128, 16, 1
	v_bfe_u32 v197, v129, 16, 1
	v_add3_u32 v196, v128, v196, s22
	v_add3_u32 v197, v129, v197, s22
	ds_write_b16_d16_hi v145, v196 offset:4624
	ds_write_b16_d16_hi v145, v197 offset:4752
	v_fma_f32 v194, v126, v128, v58
	v_fma_f32 v195, v126, v129, v10
	v_fma_f32 v194, -v127, v129, v194
	v_fma_f32 v195, v127, v128, v195
	v_bfe_u32 v196, v194, 16, 1
	v_bfe_u32 v197, v195, 16, 1
	v_add3_u32 v196, v194, v196, s22
	v_add3_u32 v197, v195, v197, s22
	ds_write_b16_d16_hi v145, v196 offset:4896
	ds_write_b16_d16_hi v145, v197 offset:5024
	v_fma_f32 v128, v126, v194, v59
	v_fma_f32 v129, v126, v195, v11
	v_fma_f32 v128, -v127, v195, v128
	v_fma_f32 v129, v127, v194, v129
	v_bfe_u32 v196, v128, 16, 1
	v_bfe_u32 v197, v129, 16, 1
	v_add3_u32 v196, v128, v196, s22
	v_add3_u32 v197, v129, v197, s22
	ds_write_b16_d16_hi v145, v196 offset:5168
	ds_write_b16_d16_hi v145, v197 offset:5296
	v_fma_f32 v194, v126, v128, v40
	v_fma_f32 v195, v126, v129, v24
	v_fma_f32 v194, -v127, v129, v194
	v_fma_f32 v195, v127, v128, v195
	v_bfe_u32 v196, v194, 16, 1
	v_bfe_u32 v197, v195, 16, 1
	v_add3_u32 v196, v194, v196, s22
	v_add3_u32 v197, v195, v197, s22
	ds_write_b16_d16_hi v145, v196 offset:5440
	ds_write_b16_d16_hi v145, v197 offset:5568
	v_fma_f32 v128, v126, v194, v41
	v_fma_f32 v129, v126, v195, v25
	v_fma_f32 v128, -v127, v195, v128
	v_fma_f32 v129, v127, v194, v129
	v_bfe_u32 v196, v128, 16, 1
	v_bfe_u32 v197, v129, 16, 1
	v_add3_u32 v196, v128, v196, s22
	v_add3_u32 v197, v129, v197, s22
	ds_write_b16_d16_hi v145, v196 offset:5712
	ds_write_b16_d16_hi v145, v197 offset:5840
	v_fma_f32 v194, v126, v128, v42
	v_fma_f32 v195, v126, v129, v26
	v_fma_f32 v194, -v127, v129, v194
	v_fma_f32 v195, v127, v128, v195
	v_bfe_u32 v196, v194, 16, 1
	v_bfe_u32 v197, v195, 16, 1
	v_add3_u32 v196, v194, v196, s22
	v_add3_u32 v197, v195, v197, s22
	ds_write_b16_d16_hi v145, v196 offset:5984
	ds_write_b16_d16_hi v145, v197 offset:6112
	v_fma_f32 v128, v126, v194, v43
	v_fma_f32 v129, v126, v195, v27
	v_fma_f32 v128, -v127, v195, v128
	v_fma_f32 v129, v127, v194, v129
	v_bfe_u32 v196, v128, 16, 1
	v_bfe_u32 v197, v129, 16, 1
	v_add3_u32 v196, v128, v196, s22
	v_add3_u32 v197, v129, v197, s22
	ds_write_b16_d16_hi v145, v196 offset:6256
	ds_write_b16_d16_hi v145, v197 offset:6384
	v_fma_f32 v194, v126, v128, v60
	v_fma_f32 v195, v126, v129, v12
	v_fma_f32 v194, -v127, v129, v194
	v_fma_f32 v195, v127, v128, v195
	v_bfe_u32 v196, v194, 16, 1
	v_bfe_u32 v197, v195, 16, 1
	v_add3_u32 v196, v194, v196, s22
	v_add3_u32 v197, v195, v197, s22
	ds_write_b16_d16_hi v145, v196 offset:6528
	ds_write_b16_d16_hi v145, v197 offset:6656
	v_fma_f32 v128, v126, v194, v61
	v_fma_f32 v129, v126, v195, v13
	v_fma_f32 v128, -v127, v195, v128
	v_fma_f32 v129, v127, v194, v129
	v_bfe_u32 v196, v128, 16, 1
	v_bfe_u32 v197, v129, 16, 1
	v_add3_u32 v196, v128, v196, s22
	v_add3_u32 v197, v129, v197, s22
	ds_write_b16_d16_hi v145, v196 offset:6800
	ds_write_b16_d16_hi v145, v197 offset:6928
; DI bf16_t f2bf(float x) { unsigned u = __float_as_uint(x); u += 0x7fffu + ((u >> 16) & 1u); return (bf16_t)(u >> 16); }
; template <bool PASS2>
; DI void s5_item(const Params& p, int l, int item, int lane, const bf16_t* ubuf, bf16_t* ybpre, bf16_t* xs, float* bus) {
;     ...
; #pragma unroll 4
;       for (int t = 0; t < 16; t++) {
;         const float bur = bus[lane * 17 + t], bui = bus[(64 + lane) * 17 + t];
;         const float nxr = ar * xr - ai * xi + bur, nxi = ar * xi + ai * xr + bui;
;         xr = nxr; xi = nxi;
;         if (PASS2) {
;           xs[(half * 16 + t) * XSP + lane] = f2bf(xr);
;           xs[(half * 16 + t) * XSP + 64 + lane] = f2bf(xi);
;         }
;       }
;     }
;     if (PASS2) {
;       __builtin_amdgcn_fence(__ATOMIC_RELEASE, "wavefront");
;       __builtin_amdgcn_wave_barrier();
;       __builtin_amdgcn_fence(__ATOMIC_ACQUIRE, "wavefront");
;       f32x16 acc;
; #pragma unroll
;       for (int i = 0; i < 16; i++) acc[i] = 0.f;
; #pragma unroll
;       for (int ks = 0; ks < 8; ks++) {
;         const bf16x8 xf = *(const bf16x8*)(xs + r * XSP + ks * 16 + hh * 8);
;         acc = __builtin_amdgcn_mfma_f32_32x32x16_bf16(cf[ks], xf, acc, 0, 0, 0);
;       }
	v_fma_f32 v194, v126, v128, v62
	v_fma_f32 v195, v126, v129, v14
	v_fma_f32 v194, -v127, v129, v194
	v_fma_f32 v195, v127, v128, v195
	v_bfe_u32 v196, v194, 16, 1
	v_bfe_u32 v197, v195, 16, 1
	v_add3_u32 v196, v194, v196, s22
	v_add3_u32 v197, v195, v197, s22
	ds_write_b16_d16_hi v145, v196 offset:7072
	ds_write_b16_d16_hi v145, v197 offset:7200
	v_fma_f32 v128, v126, v194, v63
	v_fma_f32 v129, v126, v195, v15
	v_fma_f32 v128, -v127, v195, v128
	v_fma_f32 v129, v127, v194, v129
	v_bfe_u32 v196, v128, 16, 1
	v_bfe_u32 v197, v129, 16, 1
	v_add3_u32 v196, v128, v196, s22
	v_add3_u32 v197, v129, v197, s22
	ds_write_b16_d16_hi v145, v196 offset:7344
	ds_write_b16_d16_hi v145, v197 offset:7472
	v_fma_f32 v194, v126, v128, v44
	v_fma_f32 v195, v126, v129, v28
	v_fma_f32 v194, -v127, v129, v194
	v_fma_f32 v195, v127, v128, v195
	v_bfe_u32 v196, v194, 16, 1
	v_bfe_u32 v197, v195, 16, 1
	v_add3_u32 v196, v194, v196, s22
	v_add3_u32 v197, v195, v197, s22
	ds_write_b16_d16_hi v145, v196 offset:7616
	ds_write_b16_d16_hi v145, v197 offset:7744
	v_fma_f32 v128, v126, v194, v45
	v_fma_f32 v129, v126, v195, v29
	v_fma_f32 v128, -v127, v195, v128
	v_fma_f32 v129, v127, v194, v129
	v_bfe_u32 v196, v128, 16, 1
	v_bfe_u32 v197, v129, 16, 1
	v_add3_u32 v196, v128, v196, s22
	v_add3_u32 v197, v129, v197, s22
	ds_write_b16_d16_hi v145, v196 offset:7888
	ds_write_b16_d16_hi v145, v197 offset:8016
	v_fma_f32 v194, v126, v128, v46
	v_fma_f32 v195, v126, v129, v30
	v_fma_f32 v194, -v127, v129, v194
	v_fma_f32 v195, v127, v128, v195
	v_bfe_u32 v196, v194, 16, 1
	v_bfe_u32 v197, v195, 16, 1
	v_add3_u32 v196, v194, v196, s22
	v_add3_u32 v197, v195, v197, s22
	ds_write_b16_d16_hi v145, v196 offset:8160
	ds_write_b16_d16_hi v145, v197 offset:8288
	v_fma_f32 v128, v126, v194, v47
	v_fma_f32 v129, v126, v195, v31
	v_fma_f32 v128, -v127, v195, v128
	v_fma_f32 v129, v127, v194, v129
	v_bfe_u32 v196, v128, 16, 1
	v_bfe_u32 v197, v129, 16, 1
	v_add3_u32 v196, v128, v196, s22
	v_add3_u32 v197, v129, v197, s22
	ds_write_b16_d16_hi v145, v196 offset:8432
	ds_write_b16_d16_hi v145, v197 offset:8560
	ds_read_b128 v[32:35], v143
	ds_read_b128 v[36:39], v143 offset:32
	ds_read_b128 v[40:43], v143 offset:64
	ds_read_b128 v[44:47], v143 offset:96
	ds_read_b128 v[48:51], v143 offset:128
	ds_read_b128 v[52:55], v143 offset:160
	ds_read_b128 v[56:59], v143 offset:192
	ds_read_b128 v[60:63], v143 offset:224
	v_mov_b32_e32 v125, v115
	s_waitcnt lgkmcnt(7)
	v_mfma_f32_32x32x16_bf16 v[0:15], v[80:83], v[32:35], 0
	s_add_i32 s2, s10, 32
	s_cmpk_gt_u32 s10, 0x5f
	s_mov_b32 s10, s2
	s_waitcnt lgkmcnt(6)
	v_mfma_f32_32x32x16_bf16 v[0:15], v[84:87], v[36:39], v[0:15]
	s_waitcnt lgkmcnt(5)
	v_mfma_f32_32x32x16_bf16 v[0:15], v[88:91], v[40:43], v[0:15]
	s_waitcnt lgkmcnt(4)
	v_mfma_f32_32x32x16_bf16 v[0:15], v[92:95], v[44:47], v[0:15]
	s_waitcnt lgkmcnt(3)
	v_mfma_f32_32x32x16_bf16 v[0:15], v[96:99], v[48:51], v[0:15]
	s_waitcnt lgkmcnt(2)
	v_mfma_f32_32x32x16_bf16 v[0:15], v[100:103], v[52:55], v[0:15]
	s_waitcnt lgkmcnt(1)
	v_mfma_f32_32x32x16_bf16 v[0:15], v[104:107], v[56:59], v[0:15]
	s_waitcnt lgkmcnt(0)
	v_mfma_f32_32x32x16_bf16 v[0:15], v[108:111], v[60:63], v[0:15]
	s_nop 11
	v_lshl_add_u64 v[10:11], v[138:139], 0, v[124:125]
	v_mov_b32_e32 v23, v2
	v_mov_b32_e32 v2, v1
	v_mov_b32_e32 v22, v0
	v_lshl_add_u64 v[8:9], v[140:141], 1, v[136:137]
	s_waitcnt vmcnt(2)
; DI bf16_t f2bf(float x) { unsigned u = __float_as_uint(x); u += 0x7fffu + ((u >> 16) & 1u); return (bf16_t)(u >> 16); }
; DI float bf2f(bf16_t b) { return __uint_as_float(((unsigned)b) << 16); }
; template <bool PASS2>
; DI void s5_item(const Params& p, int l, int item, int lane, const bf16_t* ubuf, bf16_t* ybpre, bf16_t* xs, float* bus) {
;     ...
;       const size_t tok = tok0 + tb + r;
; #pragma unroll
;       for (int q = 0; q < 2; q++) {
;         const int c0 = 8 * q + 4 * hh;
;         const uint2 uu = *(const uint2*)(ubuf + tok * 512 + g * 16 + c0);
;         const float4 dd = *(const float4*)(p.in[I_S5_D] + l * 512 + g * 16 + c0);
;         const float u0 = bf2f((bf16_t)(uu.x & 0xffff)), u1 = bf2f((bf16_t)(uu.x >> 16));
;         const float u2 = bf2f((bf16_t)(uu.y & 0xffff)), u3 = bf2f((bf16_t)(uu.y >> 16));
;         const float o0 = gelu_tanh(acc[4 * q + 0] + dd.x * u0), o1 = gelu_tanh(acc[4 * q + 1] + dd.y * u1);
;         const float o2 = gelu_tanh(acc[4 * q + 2] + dd.z * u2), o3 = gelu_tanh(acc[4 * q + 3] + dd.w * u3);
;         uint2 pk;
;         pk.x = (unsigned)f2bf(o0) | ((unsigned)f2bf(o1) << 16);
;         pk.y = (unsigned)f2bf(o2) | ((unsigned)f2bf(o3) << 16);
;         *(uint2*)(ybpre + tok * 512 + g * 16 + c0) = pk;
;       }
;     }
;   }
	v_mov_b32_e32 v16, v220
	v_mov_b32_e32 v17, v221
	v_lshlrev_b32_e32 v19, 16, v17
	v_lshlrev_b32_e32 v18, 16, v16
	v_and_b32_e32 v17, 0xffff0000, v17
	v_and_b32_e32 v16, 0xffff0000, v16
	v_mov_b32_e32 v12, v212
	v_mov_b32_e32 v13, v213
	v_mov_b32_e32 v14, v214
	v_mov_b32_e32 v15, v215
	v_mov_b32_e32 v21, v14
	v_mov_b32_e32 v14, v13
	v_pk_fma_f32 v[2:3], v[14:15], v[16:17], v[2:3]
	v_mov_b32_e32 v20, v12
	v_mul_f32_e32 v1, 0x3d372713, v2
	v_mul_f32_e32 v1, v2, v1
	v_fma_f32 v1, v2, v1, v2
	v_mul_f32_e32 v1, 0x3f4c422a, v1
	v_add_f32_e32 v1, v1, v1
	v_mul_f32_e32 v1, 0x3fb8aa3b, v1
	v_exp_f32_e32 v1, v1
	v_pk_fma_f32 v[18:19], v[20:21], v[18:19], v[22:23]
	v_mul_f32_e32 v13, 0x3d372713, v3
	v_mul_f32_e32 v0, 0x3d372713, v18
	v_add_f32_e32 v1, 1.0, v1
	v_rcp_f32_e32 v12, v1
	v_mul_f32_e32 v1, 0x3d372713, v19
	v_mul_f32_e32 v0, v18, v0
	v_mul_f32_e32 v1, v19, v1
	v_fma_f32 v0, v18, v0, v18
	v_fma_f32 v1, v19, v1, v19
	v_mul_f32_e32 v13, v3, v13
	v_mul_f32_e32 v0, 0x3f4c422a, v0
	v_mul_f32_e32 v1, 0x3f4c422a, v1
	v_fma_f32 v13, v3, v13, v3
	v_add_f32_e32 v0, v0, v0
	v_add_f32_e32 v1, v1, v1
	v_mul_f32_e32 v13, 0x3f4c422a, v13
	v_mul_f32_e32 v0, 0x3fb8aa3b, v0
	v_mul_f32_e32 v1, 0x3fb8aa3b, v1
	v_add_f32_e32 v13, v13, v13
	v_exp_f32_e32 v0, v0
	v_exp_f32_e32 v1, v1
	v_mul_f32_e32 v13, 0x3fb8aa3b, v13
	v_exp_f32_e32 v13, v13
	v_add_f32_e32 v0, 1.0, v0
	v_add_f32_e32 v1, 1.0, v1
	v_rcp_f32_e32 v0, v0
	v_rcp_f32_e32 v1, v1
	v_add_f32_e32 v13, 1.0, v13
	v_rcp_f32_e32 v13, v13
	v_pk_mul_f32 v[14:15], v[18:19], 0.5 op_sel_hi:[1,0]
	v_pk_fma_f32 v[0:1], v[0:1], 2.0, 1.0 op_sel_hi:[1,0,0] neg_lo:[1,0,0] neg_hi:[1,0,0]
	v_pk_mul_f32 v[2:3], v[2:3], 0.5 op_sel_hi:[1,0]
	v_pk_add_f32 v[0:1], v[0:1], 1.0 op_sel_hi:[1,0]
	v_pk_fma_f32 v[12:13], v[12:13], 2.0, 1.0 op_sel_hi:[1,0,0] neg_lo:[1,0,0] neg_hi:[1,0,0]
	v_pk_mul_f32 v[0:1], v[14:15], v[0:1]
	v_pk_add_f32 v[12:13], v[12:13], 1.0 op_sel_hi:[1,0]
	v_mov_b32_e32 v17, v6
	v_pk_mul_f32 v[2:3], v[2:3], v[12:13]
	v_and_b32_sdwa v12, v1, v180 dst_sel:DWORD dst_unused:UNUSED_PAD src0_sel:WORD_1 src1_sel:DWORD
	v_and_b32_sdwa v13, v0, v180 dst_sel:DWORD dst_unused:UNUSED_PAD src0_sel:WORD_1 src1_sel:DWORD
	v_add3_u32 v0, v0, v13, s22
	v_add3_u32 v1, v1, v12, s22
	v_and_b32_sdwa v12, v3, v180 dst_sel:DWORD dst_unused:UNUSED_PAD src0_sel:WORD_1 src1_sel:DWORD
	v_and_b32_sdwa v13, v2, v180 dst_sel:DWORD dst_unused:UNUSED_PAD src0_sel:WORD_1 src1_sel:DWORD
	v_add3_u32 v3, v3, v12, s22
	v_add3_u32 v2, v2, v13, s22
	v_and_b32_e32 v3, 0xffff0000, v3
	v_and_b32_e32 v2, 0xffff0000, v2
	v_or_b32_sdwa v1, v3, v1 dst_sel:DWORD dst_unused:UNUSED_PAD src0_sel:DWORD src1_sel:WORD_1
	v_or_b32_sdwa v0, v2, v0 dst_sel:DWORD dst_unused:UNUSED_PAD src0_sel:DWORD src1_sel:WORD_1
	global_store_dwordx2 v[8:9], v[0:1], off
	s_nop 0
	v_mov_b32_e32 v6, v5
	v_mov_b32_e32 v16, v4
	s_waitcnt vmcnt(2)
	v_mov_b32_e32 v0, v222
	v_mov_b32_e32 v1, v223
	v_lshlrev_b32_e32 v3, 16, v1
	v_lshlrev_b32_e32 v2, 16, v0
	v_and_b32_e32 v1, 0xffff0000, v1
	v_and_b32_e32 v0, 0xffff0000, v0
	v_mov_b32_e32 v10, v216
	v_mov_b32_e32 v11, v217
	v_mov_b32_e32 v12, v218
	v_mov_b32_e32 v13, v219
	v_mov_b32_e32 v15, v12
	v_mov_b32_e32 v12, v11
	v_pk_fma_f32 v[0:1], v[12:13], v[0:1], v[6:7]
	v_mov_b32_e32 v14, v10
	v_mul_f32_e32 v5, 0x3d372713, v0
	v_mul_f32_e32 v5, v0, v5
	v_fma_f32 v5, v0, v5, v0
	v_mul_f32_e32 v5, 0x3f4c422a, v5
	v_add_f32_e32 v5, v5, v5
	v_mul_f32_e32 v5, 0x3fb8aa3b, v5
	v_exp_f32_e32 v5, v5
	v_pk_fma_f32 v[2:3], v[14:15], v[2:3], v[16:17]
	v_add_f32_e32 v5, 1.0, v5
	v_mul_f32_e32 v4, 0x3d372713, v2
	v_rcp_f32_e32 v6, v5
	v_mul_f32_e32 v5, 0x3d372713, v3
	v_mul_f32_e32 v4, v2, v4
	v_mul_f32_e32 v5, v3, v5
	v_fma_f32 v4, v2, v4, v2
	v_fma_f32 v5, v3, v5, v3
	v_mul_f32_e32 v4, 0x3f4c422a, v4
	v_mul_f32_e32 v5, 0x3f4c422a, v5
	v_add_f32_e32 v4, v4, v4
	v_add_f32_e32 v5, v5, v5
	v_mul_f32_e32 v4, 0x3fb8aa3b, v4
	v_mul_f32_e32 v5, 0x3fb8aa3b, v5
	v_exp_f32_e32 v4, v4
	v_exp_f32_e32 v5, v5
	v_pk_mul_f32 v[2:3], v[2:3], 0.5 op_sel_hi:[1,0]
	v_add_f32_e32 v4, 1.0, v4
	v_add_f32_e32 v5, 1.0, v5
	v_rcp_f32_e32 v4, v4
	v_rcp_f32_e32 v5, v5
	s_nop 0
	v_pk_fma_f32 v[4:5], v[4:5], 2.0, 1.0 op_sel_hi:[1,0,0] neg_lo:[1,0,0] neg_hi:[1,0,0]
	s_nop 0
	v_pk_add_f32 v[4:5], v[4:5], 1.0 op_sel_hi:[1,0]
	s_nop 0
	v_pk_mul_f32 v[2:3], v[2:3], v[4:5]
	v_mul_f32_e32 v4, 0x3d372713, v1
	v_mul_f32_e32 v4, v1, v4
	v_fma_f32 v4, v1, v4, v1
	v_mul_f32_e32 v4, 0x3f4c422a, v4
	v_add_f32_e32 v4, v4, v4
	v_mul_f32_e32 v4, 0x3fb8aa3b, v4
	v_exp_f32_e32 v4, v4
	v_pk_mul_f32 v[0:1], v[0:1], 0.5 op_sel_hi:[1,0]
	v_add_f32_e32 v4, 1.0, v4
	v_rcp_f32_e32 v7, v4
	s_nop 0
	v_pk_fma_f32 v[4:5], v[6:7], 2.0, 1.0 op_sel_hi:[1,0,0] neg_lo:[1,0,0] neg_hi:[1,0,0]
	s_nop 0
	v_pk_add_f32 v[4:5], v[4:5], 1.0 op_sel_hi:[1,0]
	s_nop 0
	v_pk_mul_f32 v[0:1], v[0:1], v[4:5]
	v_and_b32_sdwa v4, v3, v180 dst_sel:DWORD dst_unused:UNUSED_PAD src0_sel:WORD_1 src1_sel:DWORD
	v_and_b32_sdwa v5, v2, v180 dst_sel:DWORD dst_unused:UNUSED_PAD src0_sel:WORD_1 src1_sel:DWORD
	v_add3_u32 v2, v2, v5, s22
	v_add3_u32 v3, v3, v4, s22
	v_and_b32_sdwa v4, v1, v180 dst_sel:DWORD dst_unused:UNUSED_PAD src0_sel:WORD_1 src1_sel:DWORD
	v_and_b32_sdwa v5, v0, v180 dst_sel:DWORD dst_unused:UNUSED_PAD src0_sel:WORD_1 src1_sel:DWORD
	v_add3_u32 v1, v1, v4, s22
	v_add3_u32 v0, v0, v5, s22
	v_and_b32_e32 v1, 0xffff0000, v1
	v_and_b32_e32 v0, 0xffff0000, v0
	v_or_b32_sdwa v1, v1, v3 dst_sel:DWORD dst_unused:UNUSED_PAD src0_sel:DWORD src1_sel:WORD_1
	v_or_b32_sdwa v0, v0, v2 dst_sel:DWORD dst_unused:UNUSED_PAD src0_sel:DWORD src1_sel:WORD_1
	global_store_dwordx2 v[8:9], v[0:1], off offset:16
	s_cbranch_scc0 .LBB0_786
	v_readlane_b32 s2, v252, 27
	v_readlane_b32 s3, v252, 28
	s_nop 0
	v_add_u32_e32 v142, s2, v142
	s_movk_i32 s2, 0x1fff
	v_cmp_lt_i32_e64 s[4:5], s2, v142
	s_or_b64 s[8:9], s[4:5], s[8:9]
	s_andn2_b64 exec, exec, s[8:9]
	s_cbranch_execnz .LBB0_659
	s_branch .LBB0_798

; DI bf16_t f2bf(float x) { unsigned u = __float_as_uint(x); u += 0x7fffu + ((u >> 16) & 1u); return (bf16_t)(u >> 16); }
; template <bool PASS2>
; DI void s5_item(const Params& p, int l, int item, int lane, const bf16_t* ubuf, bf16_t* ybpre, bf16_t* xs, float* bus) {
;     ...
;     const bf16x8 uf = *(const bf16x8*)(ubuf + (tok0 + tb + r) * 512 + g * 16 + 8 * hh);
;     f32x16 D[4];
; #pragma unroll
;     for (int mt = 0; mt < 4; mt++) {
; #pragma unroll
;       for (int i = 0; i < 16; i++) D[mt][i] = 0.f;
;       D[mt] = __builtin_amdgcn_mfma_f32_32x32x16_bf16(bf_[mt], uf, D[mt], 0, 0, 0);
;     }
; #pragma unroll
;     for (int half = 0; half < 2; half++) {
;       __builtin_amdgcn_fence(__ATOMIC_RELEASE, "wavefront");
;       __builtin_amdgcn_wave_barrier();
;       if ((r >> 4) == half) {
; #pragma unroll
;         for (int mt = 0; mt < 4; mt++)
; #pragma unroll
;           for (int i = 0; i < 16; i++)
;             bus[(32 * mt + (i & 3) + 8 * (i >> 2) + 4 * hh) * 17 + (r & 15)] = D[mt][i];
;       }
;       __builtin_amdgcn_fence(__ATOMIC_RELEASE, "wavefront");
;       __builtin_amdgcn_wave_barrier();
;       __builtin_amdgcn_fence(__ATOMIC_ACQUIRE, "wavefront");
; #pragma unroll 4
;       for (int t = 0; t < 16; t++) {
;         const float bur = bus[lane * 17 + t], bui = bus[(64 + lane) * 17 + t];
;         const float nxr = ar * xr - ai * xi + bur, nxi = ar * xi + ai * xr + bui;
;         xr = nxr; xi = nxi;
;         if (PASS2) {
;           xs[(half * 16 + t) * XSP + lane] = f2bf(xr);
;           xs[(half * 16 + t) * XSP + 64 + lane] = f2bf(xi);
;         }
;       }
.LBB0_2662:
	v_lshl_add_u64 v[140:141], v[130:131], 0, s[14:15]
	v_lshlrev_b64 v[0:1], 10, v[140:141]
	v_lshl_add_u64 v[138:139], s[0:1], 0, v[0:1]
	v_lshl_add_u64 v[0:1], v[138:139], 0, v[114:115]
	v_lshl_add_u64 v[208:209], v[0:1], 0, s[98:99]
	v_mov_b32_e32 v206, v124
	v_mov_b32_e32 v207, v115
	v_lshl_add_u64 v[206:207], v[138:139], 0, v[206:207]
	global_load_dwordx2 v[220:221], v[206:207], off
	global_load_dwordx2 v[222:223], v[206:207], off offset:16
	v_add_u32_e32 v190, 0x8800, v144
	v_add_u32_e32 v189, 0x8c00, v144
	v_add_u32_e32 v187, 0x9000, v144
	v_add_u32_e32 v188, 0x9400, v144
	v_add_u32_e32 v186, 0x9800, v144
	v_add_u32_e32 v184, 0x9c00, v144
	v_add_u32_e32 v185, 0x9e00, v144
	v_add_u32_e32 v183, 0xa000, v144
	v_add_u32_e32 v125, 0xa400, v144
	v_add_u32_e32 v181, 0xa600, v144
	v_add_u32_e32 v182, 0xa800, v144
	s_waitcnt vmcnt(4)
	v_mfma_f32_32x32x16_bf16 v[48:63], v[202:205], v[64:67], 0
	v_mfma_f32_32x32x16_bf16 v[32:47], v[202:205], v[68:71], 0
	v_mfma_f32_32x32x16_bf16 v[0:15], v[202:205], v[72:75], 0
	v_mfma_f32_32x32x16_bf16 v[16:31], v[202:205], v[76:79], 0
	global_load_dwordx4 v[202:205], v[208:209], off
	v_lshlrev_b64 v[140:141], 9, v[140:141]
	s_nop 7
	s_nop 1
	v_permlane32_swap_b32 v48, v32
	v_permlane32_swap_b32 v49, v33
	v_permlane32_swap_b32 v50, v34
	v_permlane32_swap_b32 v51, v35
	v_permlane32_swap_b32 v52, v36
	v_permlane32_swap_b32 v53, v37
	v_permlane32_swap_b32 v54, v38
	v_permlane32_swap_b32 v55, v39
	v_permlane32_swap_b32 v56, v40
	v_permlane32_swap_b32 v57, v41
	v_permlane32_swap_b32 v58, v42
	v_permlane32_swap_b32 v59, v43
	v_permlane32_swap_b32 v60, v44
	v_permlane32_swap_b32 v61, v45
	v_permlane32_swap_b32 v62, v46
	v_permlane32_swap_b32 v63, v47
	v_permlane32_swap_b32 v0, v16
	v_permlane32_swap_b32 v1, v17
	v_permlane32_swap_b32 v2, v18
	v_permlane32_swap_b32 v3, v19
	v_permlane32_swap_b32 v4, v20
	v_permlane32_swap_b32 v5, v21
	v_permlane32_swap_b32 v6, v22
	v_permlane32_swap_b32 v7, v23
	v_permlane32_swap_b32 v8, v24
	v_permlane32_swap_b32 v9, v25
	v_permlane32_swap_b32 v10, v26
	v_permlane32_swap_b32 v11, v27
	v_permlane32_swap_b32 v12, v28
	v_permlane32_swap_b32 v13, v29
	v_permlane32_swap_b32 v14, v30
	v_permlane32_swap_b32 v15, v31
	v_fma_f32 v194, v126, v128, v48
	v_fma_f32 v195, v126, v129, v0
	v_fma_f32 v194, -v127, v129, v194
	v_fma_f32 v195, v127, v128, v195
	v_bfe_u32 v196, v194, 16, 1
	v_bfe_u32 v197, v195, 16, 1
	v_add3_u32 v196, v194, v196, s6
	v_add3_u32 v197, v195, v197, s6
	ds_write_b16_d16_hi v145, v196 offset:0
	ds_write_b16_d16_hi v145, v197 offset:128
	v_fma_f32 v128, v126, v194, v49
	v_fma_f32 v129, v126, v195, v1
	v_fma_f32 v128, -v127, v195, v128
	v_fma_f32 v129, v127, v194, v129
	v_bfe_u32 v196, v128, 16, 1
	v_bfe_u32 v197, v129, 16, 1
	v_add3_u32 v196, v128, v196, s6
	v_add3_u32 v197, v129, v197, s6
	ds_write_b16_d16_hi v145, v196 offset:272
	ds_write_b16_d16_hi v145, v197 offset:400
	v_fma_f32 v194, v126, v128, v50
	v_fma_f32 v195, v126, v129, v2
	v_fma_f32 v194, -v127, v129, v194
	v_fma_f32 v195, v127, v128, v195
	v_bfe_u32 v196, v194, 16, 1
	v_bfe_u32 v197, v195, 16, 1
	v_add3_u32 v196, v194, v196, s6
	v_add3_u32 v197, v195, v197, s6
	ds_write_b16_d16_hi v145, v196 offset:544
	ds_write_b16_d16_hi v145, v197 offset:672
	v_fma_f32 v128, v126, v194, v51
	v_fma_f32 v129, v126, v195, v3
	v_fma_f32 v128, -v127, v195, v128
	v_fma_f32 v129, v127, v194, v129
	v_bfe_u32 v196, v128, 16, 1
	v_bfe_u32 v197, v129, 16, 1
	v_add3_u32 v196, v128, v196, s6
	v_add3_u32 v197, v129, v197, s6
	ds_write_b16_d16_hi v145, v196 offset:816
	ds_write_b16_d16_hi v145, v197 offset:944
	v_fma_f32 v194, v126, v128, v32
	v_fma_f32 v195, v126, v129, v16
	v_fma_f32 v194, -v127, v129, v194
	v_fma_f32 v195, v127, v128, v195
	v_bfe_u32 v196, v194, 16, 1
	v_bfe_u32 v197, v195, 16, 1
	v_add3_u32 v196, v194, v196, s6
	v_add3_u32 v197, v195, v197, s6
	ds_write_b16_d16_hi v145, v196 offset:1088
	ds_write_b16_d16_hi v145, v197 offset:1216
	v_fma_f32 v128, v126, v194, v33
	v_fma_f32 v129, v126, v195, v17
	v_fma_f32 v128, -v127, v195, v128
	v_fma_f32 v129, v127, v194, v129
	v_bfe_u32 v196, v128, 16, 1
	v_bfe_u32 v197, v129, 16, 1
	v_add3_u32 v196, v128, v196, s6
	v_add3_u32 v197, v129, v197, s6
	ds_write_b16_d16_hi v145, v196 offset:1360
	ds_write_b16_d16_hi v145, v197 offset:1488
	v_fma_f32 v194, v126, v128, v34
	v_fma_f32 v195, v126, v129, v18
	v_fma_f32 v194, -v127, v129, v194
	v_fma_f32 v195, v127, v128, v195
	v_bfe_u32 v196, v194, 16, 1
	v_bfe_u32 v197, v195, 16, 1
	v_add3_u32 v196, v194, v196, s6
	v_add3_u32 v197, v195, v197, s6
	ds_write_b16_d16_hi v145, v196 offset:1632
	ds_write_b16_d16_hi v145, v197 offset:1760
	v_fma_f32 v128, v126, v194, v35
	v_fma_f32 v129, v126, v195, v19
	v_fma_f32 v128, -v127, v195, v128
	v_fma_f32 v129, v127, v194, v129
	v_bfe_u32 v196, v128, 16, 1
	v_bfe_u32 v197, v129, 16, 1
	v_add3_u32 v196, v128, v196, s6
	v_add3_u32 v197, v129, v197, s6
	ds_write_b16_d16_hi v145, v196 offset:1904
	ds_write_b16_d16_hi v145, v197 offset:2032
	v_fma_f32 v194, v126, v128, v52
	v_fma_f32 v195, v126, v129, v4
	v_fma_f32 v194, -v127, v129, v194
	v_fma_f32 v195, v127, v128, v195
	v_bfe_u32 v196, v194, 16, 1
	v_bfe_u32 v197, v195, 16, 1
	v_add3_u32 v196, v194, v196, s6
	v_add3_u32 v197, v195, v197, s6
	ds_write_b16_d16_hi v145, v196 offset:2176
	ds_write_b16_d16_hi v145, v197 offset:2304
	v_fma_f32 v128, v126, v194, v53
	v_fma_f32 v129, v126, v195, v5
	v_fma_f32 v128, -v127, v195, v128
	v_fma_f32 v129, v127, v194, v129
	v_bfe_u32 v196, v128, 16, 1
	v_bfe_u32 v197, v129, 16, 1
	v_add3_u32 v196, v128, v196, s6
	v_add3_u32 v197, v129, v197, s6
	ds_write_b16_d16_hi v145, v196 offset:2448
; DI bf16_t f2bf(float x) { unsigned u = __float_as_uint(x); u += 0x7fffu + ((u >> 16) & 1u); return (bf16_t)(u >> 16); }
; template <bool PASS2>
; DI void s5_item(const Params& p, int l, int item, int lane, const bf16_t* ubuf, bf16_t* ybpre, bf16_t* xs, float* bus) {
;     ...
;       for (int t = 0; t < 16; t++) {
;         const float bur = bus[lane * 17 + t], bui = bus[(64 + lane) * 17 + t];
;         const float nxr = ar * xr - ai * xi + bur, nxi = ar * xi + ai * xr + bui;
;         xr = nxr; xi = nxi;
;         if (PASS2) {
;           xs[(half * 16 + t) * XSP + lane] = f2bf(xr);
;           xs[(half * 16 + t) * XSP + 64 + lane] = f2bf(xi);
;         }
;       }
	ds_write_b16_d16_hi v145, v197 offset:2576
	v_fma_f32 v194, v126, v128, v54
	v_fma_f32 v195, v126, v129, v6
	v_fma_f32 v194, -v127, v129, v194
	v_fma_f32 v195, v127, v128, v195
	v_bfe_u32 v196, v194, 16, 1
	v_bfe_u32 v197, v195, 16, 1
	v_add3_u32 v196, v194, v196, s6
	v_add3_u32 v197, v195, v197, s6
	ds_write_b16_d16_hi v145, v196 offset:2720
	ds_write_b16_d16_hi v145, v197 offset:2848
	v_fma_f32 v128, v126, v194, v55
	v_fma_f32 v129, v126, v195, v7
	v_fma_f32 v128, -v127, v195, v128
	v_fma_f32 v129, v127, v194, v129
	v_bfe_u32 v196, v128, 16, 1
	v_bfe_u32 v197, v129, 16, 1
	v_add3_u32 v196, v128, v196, s6
	v_add3_u32 v197, v129, v197, s6
	ds_write_b16_d16_hi v145, v196 offset:2992
	ds_write_b16_d16_hi v145, v197 offset:3120
	v_fma_f32 v194, v126, v128, v36
	v_fma_f32 v195, v126, v129, v20
	v_fma_f32 v194, -v127, v129, v194
	v_fma_f32 v195, v127, v128, v195
	v_bfe_u32 v196, v194, 16, 1
	v_bfe_u32 v197, v195, 16, 1
	v_add3_u32 v196, v194, v196, s6
	v_add3_u32 v197, v195, v197, s6
	ds_write_b16_d16_hi v145, v196 offset:3264
	ds_write_b16_d16_hi v145, v197 offset:3392
	v_fma_f32 v128, v126, v194, v37
	v_fma_f32 v129, v126, v195, v21
	v_fma_f32 v128, -v127, v195, v128
	v_fma_f32 v129, v127, v194, v129
	v_bfe_u32 v196, v128, 16, 1
	v_bfe_u32 v197, v129, 16, 1
	v_add3_u32 v196, v128, v196, s6
	v_add3_u32 v197, v129, v197, s6
	ds_write_b16_d16_hi v145, v196 offset:3536
	ds_write_b16_d16_hi v145, v197 offset:3664
	v_fma_f32 v194, v126, v128, v38
	v_fma_f32 v195, v126, v129, v22
	v_fma_f32 v194, -v127, v129, v194
	v_fma_f32 v195, v127, v128, v195
	v_bfe_u32 v196, v194, 16, 1
	v_bfe_u32 v197, v195, 16, 1
	v_add3_u32 v196, v194, v196, s6
	v_add3_u32 v197, v195, v197, s6
	ds_write_b16_d16_hi v145, v196 offset:3808
	ds_write_b16_d16_hi v145, v197 offset:3936
	v_fma_f32 v128, v126, v194, v39
	v_fma_f32 v129, v126, v195, v23
	v_fma_f32 v128, -v127, v195, v128
	v_fma_f32 v129, v127, v194, v129
	v_bfe_u32 v196, v128, 16, 1
	v_bfe_u32 v197, v129, 16, 1
	v_add3_u32 v196, v128, v196, s6
	v_add3_u32 v197, v129, v197, s6
	ds_write_b16_d16_hi v145, v196 offset:4080
	ds_write_b16_d16_hi v145, v197 offset:4208
	v_fma_f32 v194, v126, v128, v56
	v_fma_f32 v195, v126, v129, v8
	v_fma_f32 v194, -v127, v129, v194
	v_fma_f32 v195, v127, v128, v195
	v_bfe_u32 v196, v194, 16, 1
	v_bfe_u32 v197, v195, 16, 1
	v_add3_u32 v196, v194, v196, s6
	v_add3_u32 v197, v195, v197, s6
	ds_write_b16_d16_hi v145, v196 offset:4352
	ds_write_b16_d16_hi v145, v197 offset:4480
	v_fma_f32 v128, v126, v194, v57
	v_fma_f32 v129, v126, v195, v9
	v_fma_f32 v128, -v127, v195, v128
	v_fma_f32 v129, v127, v194, v129
	v_bfe_u32 v196, v128, 16, 1
	v_bfe_u32 v197, v129, 16, 1
	v_add3_u32 v196, v128, v196, s6
	v_add3_u32 v197, v129, v197, s6
	ds_write_b16_d16_hi v145, v196 offset:4624
	ds_write_b16_d16_hi v145, v197 offset:4752
	v_fma_f32 v194, v126, v128, v58
	v_fma_f32 v195, v126, v129, v10
	v_fma_f32 v194, -v127, v129, v194
	v_fma_f32 v195, v127, v128, v195
	v_bfe_u32 v196, v194, 16, 1
	v_bfe_u32 v197, v195, 16, 1
	v_add3_u32 v196, v194, v196, s6
	v_add3_u32 v197, v195, v197, s6
	ds_write_b16_d16_hi v145, v196 offset:4896
	ds_write_b16_d16_hi v145, v197 offset:5024
	v_fma_f32 v128, v126, v194, v59
	v_fma_f32 v129, v126, v195, v11
	v_fma_f32 v128, -v127, v195, v128
	v_fma_f32 v129, v127, v194, v129
	v_bfe_u32 v196, v128, 16, 1
	v_bfe_u32 v197, v129, 16, 1
	v_add3_u32 v196, v128, v196, s6
	v_add3_u32 v197, v129, v197, s6
	ds_write_b16_d16_hi v145, v196 offset:5168
	ds_write_b16_d16_hi v145, v197 offset:5296
	v_fma_f32 v194, v126, v128, v40
	v_fma_f32 v195, v126, v129, v24
	v_fma_f32 v194, -v127, v129, v194
	v_fma_f32 v195, v127, v128, v195
	v_bfe_u32 v196, v194, 16, 1
	v_bfe_u32 v197, v195, 16, 1
	v_add3_u32 v196, v194, v196, s6
	v_add3_u32 v197, v195, v197, s6
	ds_write_b16_d16_hi v145, v196 offset:5440
	ds_write_b16_d16_hi v145, v197 offset:5568
	v_fma_f32 v128, v126, v194, v41
	v_fma_f32 v129, v126, v195, v25
	v_fma_f32 v128, -v127, v195, v128
	v_fma_f32 v129, v127, v194, v129
	v_bfe_u32 v196, v128, 16, 1
	v_bfe_u32 v197, v129, 16, 1
	v_add3_u32 v196, v128, v196, s6
	v_add3_u32 v197, v129, v197, s6
	ds_write_b16_d16_hi v145, v196 offset:5712
	ds_write_b16_d16_hi v145, v197 offset:5840
	v_fma_f32 v194, v126, v128, v42
	v_fma_f32 v195, v126, v129, v26
	v_fma_f32 v194, -v127, v129, v194
	v_fma_f32 v195, v127, v128, v195
	v_bfe_u32 v196, v194, 16, 1
	v_bfe_u32 v197, v195, 16, 1
	v_add3_u32 v196, v194, v196, s6
	v_add3_u32 v197, v195, v197, s6
	ds_write_b16_d16_hi v145, v196 offset:5984
	ds_write_b16_d16_hi v145, v197 offset:6112
	v_fma_f32 v128, v126, v194, v43
	v_fma_f32 v129, v126, v195, v27
	v_fma_f32 v128, -v127, v195, v128
	v_fma_f32 v129, v127, v194, v129
	v_bfe_u32 v196, v128, 16, 1
	v_bfe_u32 v197, v129, 16, 1
	v_add3_u32 v196, v128, v196, s6
	v_add3_u32 v197, v129, v197, s6
	ds_write_b16_d16_hi v145, v196 offset:6256
	ds_write_b16_d16_hi v145, v197 offset:6384
	v_fma_f32 v194, v126, v128, v60
	v_fma_f32 v195, v126, v129, v12
	v_fma_f32 v194, -v127, v129, v194
	v_fma_f32 v195, v127, v128, v195
	v_bfe_u32 v196, v194, 16, 1
	v_bfe_u32 v197, v195, 16, 1
	v_add3_u32 v196, v194, v196, s6
	v_add3_u32 v197, v195, v197, s6
	ds_write_b16_d16_hi v145, v196 offset:6528
	ds_write_b16_d16_hi v145, v197 offset:6656
	v_fma_f32 v128, v126, v194, v61
	v_fma_f32 v129, v126, v195, v13
	v_fma_f32 v128, -v127, v195, v128
	v_fma_f32 v129, v127, v194, v129
	v_bfe_u32 v196, v128, 16, 1
	v_bfe_u32 v197, v129, 16, 1
	v_add3_u32 v196, v128, v196, s6
	v_add3_u32 v197, v129, v197, s6
	ds_write_b16_d16_hi v145, v196 offset:6800
	ds_write_b16_d16_hi v145, v197 offset:6928
	v_fma_f32 v194, v126, v128, v62
; DI bf16_t f2bf(float x) { unsigned u = __float_as_uint(x); u += 0x7fffu + ((u >> 16) & 1u); return (bf16_t)(u >> 16); }
; template <bool PASS2>
; DI void s5_item(const Params& p, int l, int item, int lane, const bf16_t* ubuf, bf16_t* ybpre, bf16_t* xs, float* bus) {
;     ...
;       for (int t = 0; t < 16; t++) {
;         const float bur = bus[lane * 17 + t], bui = bus[(64 + lane) * 17 + t];
;         const float nxr = ar * xr - ai * xi + bur, nxi = ar * xi + ai * xr + bui;
;         xr = nxr; xi = nxi;
;         if (PASS2) {
;           xs[(half * 16 + t) * XSP + lane] = f2bf(xr);
;           xs[(half * 16 + t) * XSP + 64 + lane] = f2bf(xi);
;         }
;       }
;     }
;     if (PASS2) {
;       __builtin_amdgcn_fence(__ATOMIC_RELEASE, "wavefront");
;       __builtin_amdgcn_wave_barrier();
;       __builtin_amdgcn_fence(__ATOMIC_ACQUIRE, "wavefront");
;       f32x16 acc;
; #pragma unroll
;       for (int i = 0; i < 16; i++) acc[i] = 0.f;
; #pragma unroll
;       for (int ks = 0; ks < 8; ks++) {
;         const bf16x8 xf = *(const bf16x8*)(xs + r * XSP + ks * 16 + hh * 8);
;         acc = __builtin_amdgcn_mfma_f32_32x32x16_bf16(cf[ks], xf, acc, 0, 0, 0);
;       }
	v_fma_f32 v195, v126, v129, v14
	v_fma_f32 v194, -v127, v129, v194
	v_fma_f32 v195, v127, v128, v195
	v_bfe_u32 v196, v194, 16, 1
	v_bfe_u32 v197, v195, 16, 1
	v_add3_u32 v196, v194, v196, s6
	v_add3_u32 v197, v195, v197, s6
	ds_write_b16_d16_hi v145, v196 offset:7072
	ds_write_b16_d16_hi v145, v197 offset:7200
	v_fma_f32 v128, v126, v194, v63
	v_fma_f32 v129, v126, v195, v15
	v_fma_f32 v128, -v127, v195, v128
	v_fma_f32 v129, v127, v194, v129
	v_bfe_u32 v196, v128, 16, 1
	v_bfe_u32 v197, v129, 16, 1
	v_add3_u32 v196, v128, v196, s6
	v_add3_u32 v197, v129, v197, s6
	ds_write_b16_d16_hi v145, v196 offset:7344
	ds_write_b16_d16_hi v145, v197 offset:7472
	v_fma_f32 v194, v126, v128, v44
	v_fma_f32 v195, v126, v129, v28
	v_fma_f32 v194, -v127, v129, v194
	v_fma_f32 v195, v127, v128, v195
	v_bfe_u32 v196, v194, 16, 1
	v_bfe_u32 v197, v195, 16, 1
	v_add3_u32 v196, v194, v196, s6
	v_add3_u32 v197, v195, v197, s6
	ds_write_b16_d16_hi v145, v196 offset:7616
	ds_write_b16_d16_hi v145, v197 offset:7744
	v_fma_f32 v128, v126, v194, v45
	v_fma_f32 v129, v126, v195, v29
	v_fma_f32 v128, -v127, v195, v128
	v_fma_f32 v129, v127, v194, v129
	v_bfe_u32 v196, v128, 16, 1
	v_bfe_u32 v197, v129, 16, 1
	v_add3_u32 v196, v128, v196, s6
	v_add3_u32 v197, v129, v197, s6
	ds_write_b16_d16_hi v145, v196 offset:7888
	ds_write_b16_d16_hi v145, v197 offset:8016
	v_fma_f32 v194, v126, v128, v46
	v_fma_f32 v195, v126, v129, v30
	v_fma_f32 v194, -v127, v129, v194
	v_fma_f32 v195, v127, v128, v195
	v_bfe_u32 v196, v194, 16, 1
	v_bfe_u32 v197, v195, 16, 1
	v_add3_u32 v196, v194, v196, s6
	v_add3_u32 v197, v195, v197, s6
	ds_write_b16_d16_hi v145, v196 offset:8160
	ds_write_b16_d16_hi v145, v197 offset:8288
	v_fma_f32 v128, v126, v194, v47
	v_fma_f32 v129, v126, v195, v31
	v_fma_f32 v128, -v127, v195, v128
	v_fma_f32 v129, v127, v194, v129
	v_bfe_u32 v196, v128, 16, 1
	v_bfe_u32 v197, v129, 16, 1
	v_add3_u32 v196, v128, v196, s6
	v_add3_u32 v197, v129, v197, s6
	ds_write_b16_d16_hi v145, v196 offset:8432
	ds_write_b16_d16_hi v145, v197 offset:8560
	ds_read_b128 v[32:35], v143
	ds_read_b128 v[36:39], v143 offset:32
	ds_read_b128 v[40:43], v143 offset:64
	ds_read_b128 v[44:47], v143 offset:96
	ds_read_b128 v[48:51], v143 offset:128
	ds_read_b128 v[52:55], v143 offset:160
	ds_read_b128 v[56:59], v143 offset:192
	ds_read_b128 v[60:63], v143 offset:224
	v_mov_b32_e32 v125, v115
	s_waitcnt lgkmcnt(7)
	v_mfma_f32_32x32x16_bf16 v[0:15], v[80:83], v[32:35], 0
	s_add_i32 s2, s14, 32
	s_cmpk_gt_u32 s14, 0x5f
	s_mov_b32 s14, s2
	s_waitcnt lgkmcnt(6)
	v_mfma_f32_32x32x16_bf16 v[0:15], v[84:87], v[36:39], v[0:15]
	s_waitcnt lgkmcnt(5)
	v_mfma_f32_32x32x16_bf16 v[0:15], v[88:91], v[40:43], v[0:15]
	s_waitcnt lgkmcnt(4)
	v_mfma_f32_32x32x16_bf16 v[0:15], v[92:95], v[44:47], v[0:15]
	s_waitcnt lgkmcnt(3)
	v_mfma_f32_32x32x16_bf16 v[0:15], v[96:99], v[48:51], v[0:15]
	s_waitcnt lgkmcnt(2)
	v_mfma_f32_32x32x16_bf16 v[0:15], v[100:103], v[52:55], v[0:15]
	s_waitcnt lgkmcnt(1)
	v_mfma_f32_32x32x16_bf16 v[0:15], v[104:107], v[56:59], v[0:15]
	s_waitcnt lgkmcnt(0)
	v_mfma_f32_32x32x16_bf16 v[0:15], v[108:111], v[60:63], v[0:15]
	s_nop 11
	v_lshl_add_u64 v[10:11], v[138:139], 0, v[124:125]
	v_mov_b32_e32 v23, v2
	v_mov_b32_e32 v2, v1
	v_mov_b32_e32 v22, v0
	v_lshl_add_u64 v[8:9], v[140:141], 1, v[136:137]
	s_waitcnt vmcnt(2)
; DI bf16_t f2bf(float x) { unsigned u = __float_as_uint(x); u += 0x7fffu + ((u >> 16) & 1u); return (bf16_t)(u >> 16); }
; DI float bf2f(bf16_t b) { return __uint_as_float(((unsigned)b) << 16); }
; template <bool PASS2>
; DI void s5_item(const Params& p, int l, int item, int lane, const bf16_t* ubuf, bf16_t* ybpre, bf16_t* xs, float* bus) {
;     ...
;       const size_t tok = tok0 + tb + r;
; #pragma unroll
;       for (int q = 0; q < 2; q++) {
;         const int c0 = 8 * q + 4 * hh;
;         const uint2 uu = *(const uint2*)(ubuf + tok * 512 + g * 16 + c0);
;         const float4 dd = *(const float4*)(p.in[I_S5_D] + l * 512 + g * 16 + c0);
;         const float u0 = bf2f((bf16_t)(uu.x & 0xffff)), u1 = bf2f((bf16_t)(uu.x >> 16));
;         const float u2 = bf2f((bf16_t)(uu.y & 0xffff)), u3 = bf2f((bf16_t)(uu.y >> 16));
;         const float o0 = gelu_tanh(acc[4 * q + 0] + dd.x * u0), o1 = gelu_tanh(acc[4 * q + 1] + dd.y * u1);
;         const float o2 = gelu_tanh(acc[4 * q + 2] + dd.z * u2), o3 = gelu_tanh(acc[4 * q + 3] + dd.w * u3);
;         uint2 pk;
;         pk.x = (unsigned)f2bf(o0) | ((unsigned)f2bf(o1) << 16);
;         pk.y = (unsigned)f2bf(o2) | ((unsigned)f2bf(o3) << 16);
;         *(uint2*)(ybpre + tok * 512 + g * 16 + c0) = pk;
;       }
	v_mov_b32_e32 v16, v220
	v_mov_b32_e32 v17, v221
	v_lshlrev_b32_e32 v19, 16, v17
	v_lshlrev_b32_e32 v18, 16, v16
	v_and_b32_e32 v17, 0xffff0000, v17
	v_and_b32_e32 v16, 0xffff0000, v16
	v_mov_b32_e32 v12, v212
	v_mov_b32_e32 v13, v213
	v_mov_b32_e32 v14, v214
	v_mov_b32_e32 v15, v215
	v_mov_b32_e32 v21, v14
	v_mov_b32_e32 v14, v13
	v_pk_fma_f32 v[2:3], v[14:15], v[16:17], v[2:3]
	v_mov_b32_e32 v20, v12
	v_mul_f32_e32 v1, 0x3d372713, v2
	v_mul_f32_e32 v1, v2, v1
	v_fma_f32 v1, v2, v1, v2
	v_mul_f32_e32 v1, 0x3f4c422a, v1
	v_add_f32_e32 v1, v1, v1
	v_mul_f32_e32 v1, 0x3fb8aa3b, v1
	v_exp_f32_e32 v1, v1
	v_pk_fma_f32 v[18:19], v[20:21], v[18:19], v[22:23]
	v_mul_f32_e32 v13, 0x3d372713, v3
	v_mul_f32_e32 v0, 0x3d372713, v18
	v_add_f32_e32 v1, 1.0, v1
	v_rcp_f32_e32 v12, v1
	v_mul_f32_e32 v1, 0x3d372713, v19
	v_mul_f32_e32 v0, v18, v0
	v_mul_f32_e32 v1, v19, v1
	v_fma_f32 v0, v18, v0, v18
	v_fma_f32 v1, v19, v1, v19
	v_mul_f32_e32 v13, v3, v13
	v_mul_f32_e32 v0, 0x3f4c422a, v0
	v_mul_f32_e32 v1, 0x3f4c422a, v1
	v_fma_f32 v13, v3, v13, v3
	v_add_f32_e32 v0, v0, v0
	v_add_f32_e32 v1, v1, v1
	v_mul_f32_e32 v13, 0x3f4c422a, v13
	v_mul_f32_e32 v0, 0x3fb8aa3b, v0
	v_mul_f32_e32 v1, 0x3fb8aa3b, v1
	v_add_f32_e32 v13, v13, v13
	v_exp_f32_e32 v0, v0
	v_exp_f32_e32 v1, v1
	v_mul_f32_e32 v13, 0x3fb8aa3b, v13
	v_exp_f32_e32 v13, v13
	v_add_f32_e32 v0, 1.0, v0
	v_add_f32_e32 v1, 1.0, v1
	v_rcp_f32_e32 v0, v0
	v_rcp_f32_e32 v1, v1
	v_add_f32_e32 v13, 1.0, v13
	v_rcp_f32_e32 v13, v13
	v_pk_mul_f32 v[14:15], v[18:19], 0.5 op_sel_hi:[1,0]
	v_pk_fma_f32 v[0:1], v[0:1], 2.0, 1.0 op_sel_hi:[1,0,0] neg_lo:[1,0,0] neg_hi:[1,0,0]
	v_pk_mul_f32 v[2:3], v[2:3], 0.5 op_sel_hi:[1,0]
	v_pk_add_f32 v[0:1], v[0:1], 1.0 op_sel_hi:[1,0]
	v_pk_fma_f32 v[12:13], v[12:13], 2.0, 1.0 op_sel_hi:[1,0,0] neg_lo:[1,0,0] neg_hi:[1,0,0]
	v_pk_mul_f32 v[0:1], v[14:15], v[0:1]
	v_pk_add_f32 v[12:13], v[12:13], 1.0 op_sel_hi:[1,0]
	v_mov_b32_e32 v17, v6
	v_pk_mul_f32 v[2:3], v[2:3], v[12:13]
	v_and_b32_sdwa v12, v1, v180 dst_sel:DWORD dst_unused:UNUSED_PAD src0_sel:WORD_1 src1_sel:DWORD
	v_and_b32_sdwa v13, v0, v180 dst_sel:DWORD dst_unused:UNUSED_PAD src0_sel:WORD_1 src1_sel:DWORD
	v_add3_u32 v0, v0, v13, s6
	v_add3_u32 v1, v1, v12, s6
	v_and_b32_sdwa v12, v3, v180 dst_sel:DWORD dst_unused:UNUSED_PAD src0_sel:WORD_1 src1_sel:DWORD
	v_and_b32_sdwa v13, v2, v180 dst_sel:DWORD dst_unused:UNUSED_PAD src0_sel:WORD_1 src1_sel:DWORD
	v_add3_u32 v3, v3, v12, s6
	v_add3_u32 v2, v2, v13, s6
	v_and_b32_e32 v3, 0xffff0000, v3
	v_and_b32_e32 v2, 0xffff0000, v2
	v_or_b32_sdwa v1, v3, v1 dst_sel:DWORD dst_unused:UNUSED_PAD src0_sel:DWORD src1_sel:WORD_1
	v_or_b32_sdwa v0, v2, v0 dst_sel:DWORD dst_unused:UNUSED_PAD src0_sel:DWORD src1_sel:WORD_1
	global_store_dwordx2 v[8:9], v[0:1], off
	s_nop 0
	v_mov_b32_e32 v6, v5
	v_mov_b32_e32 v16, v4
	s_waitcnt vmcnt(2)
	v_mov_b32_e32 v0, v222
	v_mov_b32_e32 v1, v223
	v_lshlrev_b32_e32 v3, 16, v1
	v_lshlrev_b32_e32 v2, 16, v0
	v_and_b32_e32 v1, 0xffff0000, v1
	v_and_b32_e32 v0, 0xffff0000, v0
	v_mov_b32_e32 v10, v216
	v_mov_b32_e32 v11, v217
	v_mov_b32_e32 v12, v218
	v_mov_b32_e32 v13, v219
	v_mov_b32_e32 v15, v12
	v_mov_b32_e32 v12, v11
	v_pk_fma_f32 v[0:1], v[12:13], v[0:1], v[6:7]
	v_mov_b32_e32 v14, v10
	v_mul_f32_e32 v5, 0x3d372713, v0
	v_mul_f32_e32 v5, v0, v5
	v_fma_f32 v5, v0, v5, v0
	v_mul_f32_e32 v5, 0x3f4c422a, v5
	v_add_f32_e32 v5, v5, v5
	v_mul_f32_e32 v5, 0x3fb8aa3b, v5
	v_exp_f32_e32 v5, v5
	v_pk_fma_f32 v[2:3], v[14:15], v[2:3], v[16:17]
	v_add_f32_e32 v5, 1.0, v5
	v_mul_f32_e32 v4, 0x3d372713, v2
	v_rcp_f32_e32 v6, v5
	v_mul_f32_e32 v5, 0x3d372713, v3
	v_mul_f32_e32 v4, v2, v4
	v_mul_f32_e32 v5, v3, v5
	v_fma_f32 v4, v2, v4, v2
	v_fma_f32 v5, v3, v5, v3
	v_mul_f32_e32 v4, 0x3f4c422a, v4
	v_mul_f32_e32 v5, 0x3f4c422a, v5
	v_add_f32_e32 v4, v4, v4
	v_add_f32_e32 v5, v5, v5
	v_mul_f32_e32 v4, 0x3fb8aa3b, v4
	v_mul_f32_e32 v5, 0x3fb8aa3b, v5
	v_exp_f32_e32 v4, v4
	v_exp_f32_e32 v5, v5
	v_pk_mul_f32 v[2:3], v[2:3], 0.5 op_sel_hi:[1,0]
	v_add_f32_e32 v4, 1.0, v4
	v_add_f32_e32 v5, 1.0, v5
	v_rcp_f32_e32 v4, v4
	v_rcp_f32_e32 v5, v5
	s_nop 0
	v_pk_fma_f32 v[4:5], v[4:5], 2.0, 1.0 op_sel_hi:[1,0,0] neg_lo:[1,0,0] neg_hi:[1,0,0]
	s_nop 0
	v_pk_add_f32 v[4:5], v[4:5], 1.0 op_sel_hi:[1,0]
	s_nop 0
	v_pk_mul_f32 v[2:3], v[2:3], v[4:5]
	v_mul_f32_e32 v4, 0x3d372713, v1
	v_mul_f32_e32 v4, v1, v4
	v_fma_f32 v4, v1, v4, v1
	v_mul_f32_e32 v4, 0x3f4c422a, v4
	v_add_f32_e32 v4, v4, v4
	v_mul_f32_e32 v4, 0x3fb8aa3b, v4
	v_exp_f32_e32 v4, v4
	v_pk_mul_f32 v[0:1], v[0:1], 0.5 op_sel_hi:[1,0]
	v_add_f32_e32 v4, 1.0, v4
	v_rcp_f32_e32 v7, v4
	s_nop 0
	v_pk_fma_f32 v[4:5], v[6:7], 2.0, 1.0 op_sel_hi:[1,0,0] neg_lo:[1,0,0] neg_hi:[1,0,0]
	s_nop 0
	v_pk_add_f32 v[4:5], v[4:5], 1.0 op_sel_hi:[1,0]
	s_nop 0
	v_pk_mul_f32 v[0:1], v[0:1], v[4:5]
	v_and_b32_sdwa v4, v3, v180 dst_sel:DWORD dst_unused:UNUSED_PAD src0_sel:WORD_1 src1_sel:DWORD
	v_and_b32_sdwa v5, v2, v180 dst_sel:DWORD dst_unused:UNUSED_PAD src0_sel:WORD_1 src1_sel:DWORD
	v_add3_u32 v2, v2, v5, s6
	v_add3_u32 v3, v3, v4, s6
	v_and_b32_sdwa v4, v1, v180 dst_sel:DWORD dst_unused:UNUSED_PAD src0_sel:WORD_1 src1_sel:DWORD
	v_and_b32_sdwa v5, v0, v180 dst_sel:DWORD dst_unused:UNUSED_PAD src0_sel:WORD_1 src1_sel:DWORD
	v_add3_u32 v1, v1, v4, s6
	v_add3_u32 v0, v0, v5, s6
	v_and_b32_e32 v1, 0xffff0000, v1
	v_and_b32_e32 v0, 0xffff0000, v0
	v_or_b32_sdwa v1, v1, v3 dst_sel:DWORD dst_unused:UNUSED_PAD src0_sel:DWORD src1_sel:WORD_1
	v_or_b32_sdwa v0, v0, v2 dst_sel:DWORD dst_unused:UNUSED_PAD src0_sel:DWORD src1_sel:WORD_1
	global_store_dwordx2 v[8:9], v[0:1], off offset:16
	s_cbranch_scc0 .LBB0_2662
	v_readlane_b32 s0, v252, 27
	v_readlane_b32 s1, v252, 28
	s_nop 0
	v_add_u32_e32 v142, s0, v142
	s_movk_i32 s0, 0x1fff
	v_cmp_lt_i32_e64 s[0:1], s0, v142
	s_or_b64 s[12:13], s[0:1], s[12:13]
	s_andn2_b64 exec, exec, s[12:13]
	s_cbranch_execnz .LBB0_2535
	s_branch .LBB0_2674
